# non-temporal hint on the attention-combine's read-once branch-output loads
# speedup vs baseline: 1.0061x; 1.0061x over previous
; __device__ __forceinline__ int tid_fresh() { int t = threadIdx.x; asm volatile("" : "+v"(t)); return t; }
; __device__ __forceinline__ int bid_fresh() { int t = blockIdx.x; asm volatile("" : "+s"(t)); return t; }
; __device__ __forceinline__ void cb_load(CbTok& k, const bf16_t* ob, const float* lse, int t, int lane) {
; #pragma unroll
;     for (int g = 0; g < 3; ++g) { k.ob[g] = *(const u32x4*)(ob + ((size_t)g * T + t) * 512 + lane * 8); k.ls[g] = lse[((size_t)g * T + t) * 8 + (lane >> 3)]; }
; }
; __device__ __forceinline__ void phase_combine(PP p) {
;     const int lane = tid_fresh() & 63, gw = bid_fresh() * 8 + (tid_fresh() >> 6), NGW = gridDim.x * 8;
;     const bf16_t* ob = (const bf16_t*)(p->ws + WS_OB); const float* lse = (const float*)(p->ws + WS_LSE);
;     bf16_t* y = (bf16_t*)(p->ws + WS_YN); float* ssg = (float*)(p->ws + WS_SSG);
;     CbTok cur, nxt;
;     if (gw < T) cb_load(cur, ob, lse, gw, lane);
;     for (int t = gw; t < T; t += NGW) {
;         const bool more = (t + NGW) < T;
;         if (more) cb_load(nxt, ob, lse, t + NGW, lane);
.LBB0_718:
	s_mov_b64 s[12:13], s[0:1]
	v_mov_b32_e32 v0, v222
	s_mov_b32 s2, s30
	v_mov_b32_e32 v2, v222
	s_lshl_b32 s2, s2, 3
	s_movk_i32 s3, 0x2000
	v_ashrrev_i32_e32 v14, 6, v2
	v_add_u32_e32 v26, s2, v14
	v_cmp_gt_i32_e32 vcc, s3, v26
	s_and_saveexec_b64 s[8:9], vcc
	s_cbranch_execz .LBB0_725
	s_load_dwordx2 s[12:13], s[12:13], 0x110
	v_and_b32_e32 v22, 63, v0
	v_lshrrev_b32_e32 v4, 1, v0
	v_lshlrev_b32_e32 v0, 4, v22
	s_mov_b64 s[16:17], 0x24600000
	s_waitcnt lgkmcnt(0)
	v_lshl_add_u64 v[2:3], s[12:13], 0, v[0:1]
	v_and_b32_e32 v16, 28, v4
	v_mov_b32_e32 v17, v1
	v_ashrrev_i32_e32 v27, 31, v26
	v_lshl_add_u64 v[10:11], v[2:3], 0, s[16:17]
	v_lshl_add_u64 v[2:3], s[12:13], 0, v[16:17]
	s_mov_b64 s[16:17], 0x25e00000
	v_lshl_add_u64 v[12:13], v[2:3], 0, s[16:17]
	v_lshlrev_b64 v[2:3], 10, v[26:27]
	v_lshlrev_b64 v[4:5], 5, v[26:27]
	v_lshl_add_u64 v[2:3], v[10:11], 0, v[2:3]
	v_lshl_add_u64 v[6:7], v[12:13], 0, v[4:5]
	s_mov_b64 s[16:17], 0x2000
	global_load_dwordx4 v[2:5], v[2:3], off nt
	s_nop 0
	global_load_dword v43, v[6:7], off
	v_lshl_add_u64 v[6:7], v[26:27], 0, s[16:17]
	v_lshlrev_b64 v[8:9], 10, v[6:7]
	v_lshlrev_b64 v[6:7], 5, v[6:7]
	v_lshl_add_u64 v[8:9], v[10:11], 0, v[8:9]
	v_lshl_add_u64 v[18:19], v[12:13], 0, v[6:7]
	s_mov_b64 s[16:17], 0x4000
	global_load_dwordx4 v[6:9], v[8:9], off nt
	s_nop 0
	global_load_dword v44, v[18:19], off
	v_lshl_add_u64 v[18:19], v[26:27], 0, s[16:17]
	v_lshlrev_b64 v[20:21], 10, v[18:19]
	v_lshl_add_u64 v[10:11], v[10:11], 0, v[20:21]
	v_lshlrev_b64 v[18:19], 5, v[18:19]
	v_lshl_add_u64 v[18:19], v[12:13], 0, v[18:19]
	global_load_dwordx4 v[10:13], v[10:11], off nt
	s_nop 0
	global_load_dword v45, v[18:19], off
	v_and_b32_e32 v15, 64, v226
	v_add_u32_e32 v15, 64, v15
	v_xor_b32_e32 v17, 1, v226
	v_cmp_lt_i32_e32 vcc, v17, v15
	s_ashr_i32 s3, s2, 31
	v_cmp_gt_u32_e64 s[38:39], 8, v22
	v_cndmask_b32_e32 v17, v226, v17, vcc
	v_lshlrev_b32_e32 v27, 2, v17
	v_xor_b32_e32 v17, 2, v226
	v_cmp_lt_i32_e32 vcc, v17, v15
	v_cmp_eq_u32_e64 s[40:41], 0, v22
	v_lshlrev_b32_e32 v22, 2, v22
	v_cndmask_b32_e32 v17, v226, v17, vcc
	v_lshlrev_b32_e32 v36, 2, v17
	v_xor_b32_e32 v17, 4, v226
	v_cmp_lt_i32_e32 vcc, v17, v15
	v_mov_b32_e32 v23, v1
	s_mov_b64 s[16:17], 0x3a9c4060
	v_cndmask_b32_e32 v17, v226, v17, vcc
	v_lshlrev_b32_e32 v37, 2, v17
	v_xor_b32_e32 v17, 8, v226
	v_cmp_lt_i32_e32 vcc, v17, v15
	s_nop 1
	v_cndmask_b32_e32 v17, v226, v17, vcc
	v_lshlrev_b32_e32 v38, 2, v17
	v_xor_b32_e32 v17, 16, v226
	v_cmp_lt_i32_e32 vcc, v17, v15
	s_nop 1
	v_cndmask_b32_e32 v17, v226, v17, vcc
	v_lshlrev_b32_e32 v39, 2, v17
	v_xor_b32_e32 v17, 32, v226
	v_cmp_lt_i32_e32 vcc, v17, v15
	s_nop 1
	v_cndmask_b32_e32 v15, v226, v17, vcc
	v_lshlrev_b32_e32 v40, 2, v15
	v_ashrrev_i32_e32 v15, 31, v14
	v_lshl_add_u64 v[18:19], v[14:15], 0, s[2:3]
	v_lshlrev_b64 v[20:21], 7, v[18:19]
	v_lshl_add_u64 v[20:21], v[20:21], 0, v[22:23]
	v_lshlrev_b64 v[18:19], 12, v[18:19]
	v_lshl_add_u64 v[28:29], v[20:21], 0, s[16:17]
	v_or_b32_e32 v18, v18, v0
	s_mov_b64 s[16:17], 0x25ec0c00
	v_lshl_add_u64 v[30:31], v[18:19], 0, s[16:17]
	v_readlane_b32 s16, v255, 5
	s_add_i32 s2, s2, s16
	v_add_u32_e32 v14, s2, v14
	v_ashrrev_i32_e32 v15, 31, v14
	v_lshlrev_b64 v[32:33], 5, v[14:15]
	v_lshlrev_b64 v[34:35], 10, v[14:15]
	v_or_b32_e32 v32, v32, v16
	v_or_b32_e32 v34, v34, v0
	s_mov_b64 s[2:3], 0
	v_readlane_b32 s17, v255, 6
	s_branch .LBB0_721

; __device__ __forceinline__ void cb_load(CbTok& k, const bf16_t* ob, const float* lse, int t, int lane) {
; #pragma unroll
;     for (int g = 0; g < 3; ++g) { k.ob[g] = *(const u32x4*)(ob + ((size_t)g * T + t) * 512 + lane * 8); k.ls[g] = lse[((size_t)g * T + t) * 8 + (lane >> 3)]; }
; }
; __device__ __forceinline__ void phase_combine(PP p) {
;     ...
;     for (int t = gw; t < T; t += NGW) {
;         const bool more = (t + NGW) < T;
;         if (more) cb_load(nxt, ob, lse, t + NGW, lane);
.LBB0_721:
	v_readlane_b32 s16, v255, 5
	s_movk_i32 s14, 0x2000
	v_readlane_b32 s17, v255, 6
	v_add_u32_e32 v26, s16, v26
	v_cmp_gt_i32_e32 vcc, s14, v26
	s_movk_i32 s14, 0x1fff
	v_cmp_lt_i32_e64 s[42:43], s14, v26
	s_and_saveexec_b64 s[20:21], vcc
	s_cbranch_execz .LBB0_723
	v_lshl_add_u64 v[22:23], s[12:13], 0, v[34:35]
	v_add_co_u32_e32 v14, vcc, 0x24600000, v22
	v_lshl_add_u64 v[24:25], s[12:13], 0, v[32:33]
	s_nop 0
	v_addc_co_u32_e32 v15, vcc, 0, v23, vcc
	v_add_co_u32_e32 v18, vcc, 0x25e00000, v24
	s_nop 1
	v_addc_co_u32_e32 v19, vcc, 0, v25, vcc
	global_load_dwordx4 v[14:17], v[14:15], off nt
	s_nop 0
	global_load_dword v0, v[18:19], off
	v_add_co_u32_e32 v18, vcc, 0x24e00000, v22
	s_nop 1
	v_addc_co_u32_e32 v19, vcc, 0, v23, vcc
	v_add_co_u32_e32 v46, vcc, 0x25e40000, v24
	s_nop 1
	v_addc_co_u32_e32 v47, vcc, 0, v25, vcc
	v_add_co_u32_e32 v22, vcc, 0x25600000, v22
	global_load_dwordx4 v[18:21], v[18:19], off nt
	s_nop 0
	global_load_dword v41, v[46:47], off
	v_addc_co_u32_e32 v23, vcc, 0, v23, vcc
	v_add_co_u32_e32 v46, vcc, 0x25e80000, v24
	s_nop 1
	v_addc_co_u32_e32 v47, vcc, 0, v25, vcc
	global_load_dwordx4 v[22:25], v[22:23], off nt
	s_nop 0
	global_load_dword v42, v[46:47], off
